# P3: dropped the two workgroup barriers around the wave-private Pt output staging (each wave only touches its own 16 rows of Pt; LDS ops of one wave are in order)
# baseline (speedup 1.0000x reference)
; #define LAS __attribute__((address_space(3)))
; __device__ __forceinline__ f32x4 mfma16(bf16x8 a, bf16x8 b, f32x4 c) { return __builtin_amdgcn_mfma_f32_16x16x32_bf16(a, b, c, 0, 0, 0); }
; #define LBAR() asm volatile("s_waitcnt lgkmcnt(0)\n\ts_barrier" ::: "memory")
; #define OPQ_ALL() do { asm volatile("" : "+v"(g), "+v"(l15), "+v"(q4), "+v"(p)); } while (0)
; __device__ __forceinline__ void ret_phase(const Params& P, LAS unsigned char* lds, int tid, int lane, int wave, int bid, int G) {
;     ...
;         LBAR();
;         OPQ_ALL();
;         f32x4 o[8];
; #pragma unroll
;         for (int t = 0; t < 8; ++t) o[t] = (f32x4){0.f, 0.f, 0.f, 0.f};
;         u32x4 grv[4];
; #pragma unroll
;         for (int it = 0; it < 4; ++it) grv[it] = *(const u32x4*)(GR + (tokc + w16 + 4 * it + g) * 512 + h * 128 + 8 * l15);
; #pragma unroll
;         for (int t = 0; t < 8; ++t)
; #pragma unroll
;             for (int ks = 0; ks < 4; ++ks) { o[t] = mfma16(qf[ks], *(const LAS bf16x8*)(Qt + off256(16 * t + l15, 4 * ks + g)), o[t]); }
;         float wb[4];
; #pragma unroll
;         for (int i = 0; i < 4; ++i) { const float pos = (float)(w16 + 4 * g + i); const float wf = exp2f(lgf2 * (pos + 1.f)); wb[i] = exp2f(lgb2 * (128.f - pos)); const float rt = wf / wb[i];
; #pragma unroll
;             for (int t = 0; t < 8; ++t) o[t][i] *= rt; }
.LBB0_383:
	s_waitcnt lgkmcnt(0)
	s_barrier
	s_ashr_i32 s41, s40, 31
	v_lshlrev_b32_e32 v66, 2, v1
	v_and_b32_e32 v86, 12, v66
	v_bfe_u32 v87, v1, 2, 2
	v_lshl_add_u32 v88, v1, 8, 0
	v_bitop3_b32 v66, v86, v118, v87 bitop3:0x36
	v_lshl_add_u32 v135, v66, 4, v88
	ds_read_b128 v[66:69], v135
	ds_read_b128 v[70:73], v135 offset:4096
	v_add_u32_e32 v74, 4, v118
	v_bitop3_b32 v74, v86, v74, v87 bitop3:0x36
	v_lshl_add_u32 v168, v74, 4, v88
	s_waitcnt lgkmcnt(1)
	v_mfma_f32_16x16x32_bf16 v[66:69], v[58:61], v[66:69], 0
	ds_read_b128 v[74:77], v168
	ds_read_b128 v[78:81], v168 offset:4096
	v_lshl_add_u32 v102, v118, 2, s46
	v_cvt_f32_i32_e32 v103, v102
	s_waitcnt lgkmcnt(1)
	v_mfma_f32_16x16x32_bf16 v[66:69], v[54:57], v[74:77], v[66:69]
	v_add_u32_e32 v74, 8, v118
	v_bitop3_b32 v74, v86, v74, v87 bitop3:0x36
	v_lshl_add_u32 v169, v74, 4, v88
	ds_read_b128 v[74:77], v169
	ds_read_b128 v[82:85], v169 offset:4096
	s_waitcnt lgkmcnt(1)
	v_mfma_f32_16x16x32_bf16 v[66:69], v[62:65], v[74:77], v[66:69]
	v_add_u32_e32 v74, 12, v118
	v_bitop3_b32 v74, v86, v74, v87 bitop3:0x36
	v_lshl_add_u32 v170, v74, 4, v88
	ds_read_b128 v[74:77], v170
	ds_read_b128 v[86:89], v170 offset:4096
	s_waitcnt lgkmcnt(1)
	v_mfma_f32_16x16x32_bf16 v[74:77], v[50:53], v[74:77], v[66:69]
	v_add_f32_e32 v119, 1.0, v103
	v_mul_f32_e32 v171, v105, v119
	v_cmp_gt_f32_e32 vcc, s52, v171
	v_mfma_f32_16x16x32_bf16 v[66:69], v[58:61], v[70:73], 0
	v_sub_f32_e32 v103, 0x43000000, v103
	v_cndmask_b32_e32 v171, 0, v133, vcc
	s_lshl_b64 s[40:41], s[40:41], 7
	v_mfma_f32_16x16x32_bf16 v[66:69], v[54:57], v[78:81], v[66:69]
	v_mfma_f32_16x16x32_bf16 v[66:69], v[62:65], v[82:85], v[66:69]
	s_waitcnt lgkmcnt(0)
	v_mfma_f32_16x16x32_bf16 v[70:73], v[50:53], v[86:89], v[66:69]
	s_nop 5
	ds_read_b128 v[66:69], v135 offset:8192
	ds_read_b128 v[78:81], v135 offset:12288
	ds_read_b128 v[82:85], v168 offset:8192
	ds_read_b128 v[86:89], v168 offset:12288
	s_waitcnt lgkmcnt(3)
	v_mfma_f32_16x16x32_bf16 v[66:69], v[58:61], v[66:69], 0
	s_waitcnt lgkmcnt(1)
	v_mfma_f32_16x16x32_bf16 v[66:69], v[54:57], v[82:85], v[66:69]
	ds_read_b128 v[82:85], v169 offset:8192
	ds_read_b128 v[90:93], v169 offset:12288
	s_waitcnt lgkmcnt(1)
	v_mfma_f32_16x16x32_bf16 v[66:69], v[62:65], v[82:85], v[66:69]
	ds_read_b128 v[82:85], v170 offset:8192
	ds_read_b128 v[94:97], v170 offset:12288
	ds_read_b128 v[98:101], v135 offset:16384
	ds_read_b128 v[122:125], v135 offset:20480
	s_waitcnt lgkmcnt(3)
	v_mfma_f32_16x16x32_bf16 v[82:85], v[50:53], v[82:85], v[66:69]
	v_mfma_f32_16x16x32_bf16 v[66:69], v[58:61], v[78:81], 0
	v_mfma_f32_16x16x32_bf16 v[66:69], v[54:57], v[86:89], v[66:69]
	ds_read_b128 v[86:89], v168 offset:16384
	ds_read_b128 v[136:139], v168 offset:20480
	ds_read_b128 v[140:143], v169 offset:16384
	ds_read_b128 v[144:147], v169 offset:20480
	v_mfma_f32_16x16x32_bf16 v[66:69], v[62:65], v[90:93], v[66:69]
	ds_read_b128 v[90:93], v170 offset:16384
	ds_read_b128 v[148:151], v170 offset:20480
	ds_read_b128 v[152:155], v135 offset:24576
	ds_read_b128 v[156:159], v135 offset:28672
	s_waitcnt lgkmcnt(10)
	v_mfma_f32_16x16x32_bf16 v[78:81], v[50:53], v[94:97], v[66:69]
	s_nop 2
	ds_read_b128 v[66:69], v168 offset:24576
	ds_read_b128 v[160:163], v168 offset:28672
	s_waitcnt lgkmcnt(11)
	v_mfma_f32_16x16x32_bf16 v[94:97], v[58:61], v[98:101], 0
	ds_read_b128 v[98:101], v169 offset:24576
	ds_read_b128 v[164:167], v169 offset:28672
	s_waitcnt lgkmcnt(11)
	v_mfma_f32_16x16x32_bf16 v[86:89], v[54:57], v[86:89], v[94:97]
	s_nop 3
	v_cndmask_b32_e32 v94, 0, v132, vcc
	v_fmac_f32_e32 v94, v105, v119
	v_exp_f32_e32 v119, v94
	s_waitcnt lgkmcnt(9)
	v_mfma_f32_16x16x32_bf16 v[86:89], v[62:65], v[140:143], v[86:89]
	ds_read_b128 v[94:97], v170 offset:24576
	ds_read_b128 v[140:143], v170 offset:28672
	v_ldexp_f32 v119, v119, v171
	v_mul_f32_e32 v171, v104, v103
	v_cmp_gt_f32_e32 vcc, s52, v171
	s_waitcnt lgkmcnt(9)
	v_mfma_f32_16x16x32_bf16 v[90:93], v[50:53], v[90:93], v[86:89]
	v_mfma_f32_16x16x32_bf16 v[86:89], v[58:61], v[122:125], 0
	v_cndmask_b32_e32 v122, 0, v132, vcc
	v_fmac_f32_e32 v122, v104, v103
	v_or_b32_e32 v103, 1, v102
	v_cvt_f32_i32_e32 v103, v103
	v_cndmask_b32_e32 v123, 0, v133, vcc
	v_mfma_f32_16x16x32_bf16 v[86:89], v[54:57], v[136:139], v[86:89]
	v_exp_f32_e32 v122, v122
	v_add_f32_e32 v124, 1.0, v103
	v_mul_f32_e32 v125, v105, v124
	v_cmp_gt_f32_e32 vcc, s52, v125
	s_waitcnt lgkmcnt(7)
	v_mfma_f32_16x16x32_bf16 v[136:139], v[58:61], v[152:155], 0
	v_ldexp_f32 v122, v122, v123
	v_cndmask_b32_e32 v125, 0, v132, vcc
	v_fmac_f32_e32 v125, v105, v124
	v_exp_f32_e32 v124, v125
	s_waitcnt lgkmcnt(5)
	v_mfma_f32_16x16x32_bf16 v[66:69], v[54:57], v[66:69], v[136:139]
	v_cndmask_b32_e32 v123, 0, v133, vcc
	v_sub_f32_e32 v103, 0x43000000, v103
	v_ldexp_f32 v124, v124, v123
	v_mul_f32_e32 v123, v104, v103
	v_cmp_gt_f32_e32 vcc, s52, v123
	s_waitcnt lgkmcnt(3)
	v_mfma_f32_16x16x32_bf16 v[66:69], v[62:65], v[98:101], v[66:69]
	v_div_scale_f32 v99, s[0:1], v122, v122, v119
	v_cndmask_b32_e32 v98, 0, v132, vcc
	v_fmac_f32_e32 v98, v104, v103
	v_exp_f32_e32 v98, v98
	v_rcp_f32_e32 v100, v99
	v_cndmask_b32_e32 v101, 0, v133, vcc
	s_waitcnt lgkmcnt(1)
; #define LAS __attribute__((address_space(3)))
; __device__ __forceinline__ f32x4 mfma16(bf16x8 a, bf16x8 b, f32x4 c) { return __builtin_amdgcn_mfma_f32_16x16x32_bf16(a, b, c, 0, 0, 0); }
; __device__ __forceinline__ void ret_phase(const Params& P, LAS unsigned char* lds, int tid, int lane, int wave, int bid, int G) {
;     ...
;             for (int ks = 0; ks < 4; ++ks) { o[t] = mfma16(qf[ks], *(const LAS bf16x8*)(Qt + off256(16 * t + l15, 4 * ks + g)), o[t]); }
;         float wb[4];
; #pragma unroll
;         for (int i = 0; i < 4; ++i) { const float pos = (float)(w16 + 4 * g + i); const float wf = exp2f(lgf2 * (pos + 1.f)); wb[i] = exp2f(lgb2 * (128.f - pos)); const float rt = wf / wb[i];
; #pragma unroll
;             for (int t = 0; t < 8; ++t) o[t][i] *= rt; }
; #pragma unroll
;         for (int t = 0; t < 8; ++t)
; #pragma unroll
;             for (int ks = 0; ks < 4; ++ks) { o[t] = mfma16(qf[ks], *(const LAS bf16x8*)(Kt + off256(16 * t + l15, 4 * ks + g)), o[t]); }
; #pragma unroll
;         for (int i = 0; i < 4; ++i)
; #pragma unroll
;             for (int t = 0; t < 8; ++t) o[t][i] *= wb[i];
	v_mfma_f32_16x16x32_bf16 v[94:97], v[50:53], v[94:97], v[66:69]
	v_ldexp_f32 v123, v98, v101
	v_fma_f32 v98, -v99, v100, 1.0
	v_fmac_f32_e32 v100, v98, v100
	v_div_scale_f32 v98, vcc, v119, v122, v119
	v_mul_f32_e32 v101, v98, v100
	v_fma_f32 v103, -v99, v101, v98
	v_fmac_f32_e32 v101, v103, v100
	v_fma_f32 v98, -v99, v101, v98
	v_div_scale_f32 v99, s[0:1], v123, v123, v124
	v_rcp_f32_e32 v103, v99
	v_div_fmas_f32 v98, v98, v100, v101
	v_div_fixup_f32 v98, v98, v122, v119
	v_mfma_f32_16x16x32_bf16 v[66:69], v[58:61], v[156:159], 0
	v_fma_f32 v100, -v99, v103, 1.0
	v_fmac_f32_e32 v103, v100, v103
	v_div_scale_f32 v100, vcc, v124, v123, v124
	v_mul_f32_e32 v101, v100, v103
	v_fma_f32 v119, -v99, v101, v100
	v_fmac_f32_e32 v101, v119, v103
	v_fma_f32 v99, -v99, v101, v100
	v_or_b32_e32 v100, 2, v102
	v_cvt_f32_i32_e32 v100, v100
	v_div_fmas_f32 v99, v99, v103, v101
	v_or_b32_e32 v102, 3, v102
	v_cvt_f32_i32_e32 v102, v102
	v_add_f32_e32 v101, 1.0, v100
	v_mul_f32_e32 v103, v105, v101
	v_cmp_gt_f32_e32 vcc, s52, v103
	v_sub_f32_e32 v100, 0x43000000, v100
	v_mul_f32_e32 v119, v104, v100
	v_cndmask_b32_e32 v103, 0, v132, vcc
	v_fmac_f32_e32 v103, v105, v101
	v_exp_f32_e32 v101, v103
	v_cndmask_b32_e32 v103, 0, v133, vcc
	v_cmp_gt_f32_e32 vcc, s52, v119
	v_div_fixup_f32 v99, v99, v123, v124
	v_mfma_f32_16x16x32_bf16 v[66:69], v[54:57], v[160:163], v[66:69]
	v_cndmask_b32_e32 v119, 0, v132, vcc
	v_fmac_f32_e32 v119, v104, v100
	v_exp_f32_e32 v100, v119
	v_add_f32_e32 v119, 1.0, v102
	v_mul_f32_e32 v124, v105, v119
	v_cmp_gt_f32_e64 s[0:1], s52, v124
	v_sub_f32_e32 v102, 0x43000000, v102
	v_mfma_f32_16x16x32_bf16 v[66:69], v[62:65], v[164:167], v[66:69]
	v_cndmask_b32_e64 v124, 0, v132, s[0:1]
	v_fmac_f32_e32 v124, v105, v119
	v_mul_f32_e32 v119, v104, v102
	v_cmp_gt_f32_e64 s[4:5], s52, v119
	v_exp_f32_e32 v105, v124
	ds_read_b128 v[136:139], v135 offset:36864
	v_cndmask_b32_e64 v119, 0, v132, s[4:5]
	v_fmac_f32_e32 v119, v104, v102
	v_exp_f32_e32 v102, v119
	v_cndmask_b32_e64 v104, 0, v133, s[0:1]
	v_ldexp_f32 v104, v105, v104
	v_cndmask_b32_e64 v105, 0, v133, s[4:5]
	v_ldexp_f32 v125, v102, v105
	v_div_scale_f32 v102, s[0:1], v125, v125, v104
	v_rcp_f32_e32 v105, v102
	v_ldexp_f32 v119, v101, v103
	v_cndmask_b32_e32 v101, 0, v133, vcc
	v_ldexp_f32 v124, v100, v101
	v_fma_f32 v100, -v102, v105, 1.0
	v_fmac_f32_e32 v105, v100, v105
	v_div_scale_f32 v100, vcc, v104, v125, v104
	v_mul_f32_e32 v101, v100, v105
	v_fma_f32 v103, -v102, v101, v100
	v_fmac_f32_e32 v101, v103, v105
	v_fma_f32 v100, -v102, v101, v100
	v_div_scale_f32 v102, s[0:1], v124, v124, v119
	v_rcp_f32_e32 v103, v102
	v_div_fmas_f32 v100, v100, v105, v101
	v_div_fixup_f32 v157, v100, v125, v104
	v_pk_mul_f32 v[74:75], v[98:99], v[74:75]
	v_fma_f32 v100, -v102, v103, 1.0
	v_fmac_f32_e32 v103, v100, v103
	v_div_scale_f32 v100, vcc, v119, v124, v119
	v_mul_f32_e32 v101, v100, v103
	v_fma_f32 v104, -v102, v101, v100
	v_fmac_f32_e32 v101, v104, v103
	v_fma_f32 v100, -v102, v101, v100
	v_div_fmas_f32 v104, v100, v103, v101
	ds_read_b128 v[100:103], v135 offset:32768
	v_div_fixup_f32 v156, v104, v124, v119
	v_pk_mul_f32 v[76:77], v[156:157], v[76:77]
	s_waitcnt lgkmcnt(2)
	v_mfma_f32_16x16x32_bf16 v[66:69], v[50:53], v[140:143], v[66:69]
	v_mul_f32_e64 v72, v156, v72
	v_mul_f32_e64 v73, v157, v73
	v_pk_mul_f32 v[70:71], v[98:99], v[70:71]
	v_pk_mul_f32 v[96:97], v[156:157], v[96:97]
	s_waitcnt lgkmcnt(0)
	v_mfma_f32_16x16x32_bf16 v[74:77], v[58:61], v[100:103], v[74:77]
	ds_read_b128 v[100:103], v168 offset:32768
	ds_read_b128 v[140:143], v168 offset:36864
	v_pk_mul_f32 v[94:95], v[98:99], v[94:95]
	s_add_u32 s0, s40, s46
	v_mfma_f32_16x16x32_bf16 v[70:73], v[58:61], v[136:139], v[70:73]
	s_addc_u32 s1, s41, 0
	v_ashrrev_i32_e32 v119, 31, v118
	s_lshl_b32 s18, s57, 8
	v_mfma_f32_16x16x32_bf16 v[86:89], v[62:65], v[144:147], v[86:89]
	v_mul_f32_e64 v68, v156, v68
	v_mul_f32_e64 v69, v157, v69
	v_pk_mul_f32 v[66:67], v[98:99], v[66:67]
	v_lshlrev_b32_e32 v152, 3, v1
	s_waitcnt lgkmcnt(1)
	v_mfma_f32_16x16x32_bf16 v[74:77], v[54:57], v[100:103], v[74:77]
	ds_read_b128 v[100:103], v169 offset:32768
	ds_read_b128 v[144:147], v169 offset:36864
	v_ashrrev_i32_e32 v153, 31, v152
	s_waitcnt lgkmcnt(2)
	v_mfma_f32_16x16x32_bf16 v[70:73], v[54:57], v[140:143], v[70:73]
	v_mfma_f32_16x16x32_bf16 v[86:89], v[50:53], v[148:151], v[86:89]
	s_waitcnt lgkmcnt(1)
	v_mfma_f32_16x16x32_bf16 v[74:77], v[62:65], v[100:103], v[74:77]
	ds_read_b128 v[100:103], v170 offset:32768
	ds_read_b128 v[148:151], v170 offset:36864
	ds_read_b128 v[136:139], v135 offset:40960
	ds_read_b128 v[140:143], v135 offset:45056
	s_waitcnt lgkmcnt(4)
	v_mfma_f32_16x16x32_bf16 v[70:73], v[62:65], v[144:147], v[70:73]
	s_waitcnt lgkmcnt(3)
	v_mfma_f32_16x16x32_bf16 v[102:105], v[50:53], v[100:103], v[74:77]
	v_lshl_add_u64 v[100:101], s[0:1], 0, v[118:119]
	s_add_u32 s0, s21, s18
	s_addc_u32 s1, s25, 0
	s_waitcnt lgkmcnt(2)
	v_mfma_f32_16x16x32_bf16 v[74:77], v[50:53], v[148:151], v[70:73]
	v_lshl_add_u64 v[158:159], v[152:153], 1, s[0:1]
	v_lshlrev_b64 v[100:101], 10, v[100:101]
	s_nop 0
	v_pk_mul_f32 v[104:105], v[124:125], v[104:105]
	v_pk_mul_f32 v[72:73], v[156:157], v[84:85]
	v_pk_mul_f32 v[70:71], v[98:99], v[82:83]
	v_pk_mul_f32 v[102:103], v[122:123], v[102:103]
	s_nop 0
	v_pk_mul_f32 v[76:77], v[124:125], v[76:77]
	s_waitcnt lgkmcnt(1)
	v_mfma_f32_16x16x32_bf16 v[70:73], v[58:61], v[136:139], v[70:73]
	ds_read_b128 v[82:85], v168 offset:40960
	ds_read_b128 v[136:139], v168 offset:45056
	v_pk_mul_f32 v[74:75], v[122:123], v[74:75]
	s_add_i32 s56, s56, s3
	s_waitcnt lgkmcnt(1)
; #define LAS __attribute__((address_space(3)))
; __device__ __forceinline__ s16x4 tr_read(const LAS unsigned char* p) { return __builtin_amdgcn_ds_read_tr16_b64_v4i16((LAS s16x4*)p); }
; __device__ __forceinline__ bf16x8 cat8(s16x4 a, s16x4 b) { return (bf16x8){a[0], a[1], a[2], a[3], b[0], b[1], b[2], b[3]}; }
; __device__ __forceinline__ f32x4 mfma16(bf16x8 a, bf16x8 b, f32x4 c) { return __builtin_amdgcn_mfma_f32_16x16x32_bf16(a, b, c, 0, 0, 0); }
; #define OPQ_ALL() do { asm volatile("" : "+v"(g), "+v"(l15), "+v"(q4), "+v"(p)); } while (0)
; __device__ __forceinline__ void ret_phase(const Params& P, LAS unsigned char* lds, int tid, int lane, int wave, int bid, int G) {
;     ...
;         u32x4 grv[4];
; #pragma unroll
;         for (int it = 0; it < 4; ++it) grv[it] = *(const u32x4*)(GR + (tokc + w16 + 4 * it + g) * 512 + h * 128 + 8 * l15);
; #pragma unroll
;         for (int t = 0; t < 8; ++t)
; #pragma unroll
;             for (int ks = 0; ks < 4; ++ks) { o[t] = mfma16(qf[ks], *(const LAS bf16x8*)(Qt + off256(16 * t + l15, 4 * ks + g)), o[t]); }
;         float wb[4];
; #pragma unroll
;         for (int i = 0; i < 4; ++i) { const float pos = (float)(w16 + 4 * g + i); const float wf = exp2f(lgf2 * (pos + 1.f)); wb[i] = exp2f(lgb2 * (128.f - pos)); const float rt = wf / wb[i];
; #pragma unroll
;             for (int t = 0; t < 8; ++t) o[t][i] *= rt; }
; #pragma unroll
;         for (int t = 0; t < 8; ++t)
; #pragma unroll
;             for (int ks = 0; ks < 4; ++ks) { o[t] = mfma16(qf[ks], *(const LAS bf16x8*)(Kt + off256(16 * t + l15, 4 * ks + g)), o[t]); }
; #pragma unroll
;         for (int i = 0; i < 4; ++i)
; #pragma unroll
;             for (int t = 0; t < 8; ++t) o[t][i] *= wb[i];
;         OPQ_ALL();
; #pragma unroll
;         for (int ks = 0; ks < 4; ++ks) {
;             const bf16x8 pa = *(const LAS bf16x8*)(Pt + off256(w16 + l15, 4 * ks + g));
;             const unsigned r0 = 32 * ks + 8 * g + q4, r1 = r0 + 4;
; #pragma unroll
;             for (int t = 0; t < 8; ++t) { const unsigned ch = 2 * t + (p >> 1);
;                 const bf16x8 vb = cat8(tr_read(Vt + off256(r0, ch) + 8 * (p & 1)), tr_read(Vt + off256(r1, ch) + 8 * (p & 1)));
;                 o[t] = mfma16(pa, vb, o[t]); }
	v_mfma_f32_16x16x32_bf16 v[70:73], v[54:57], v[82:85], v[70:73]
	ds_read_b128 v[82:85], v169 offset:40960
	ds_read_b128 v[144:147], v169 offset:45056
	s_waitcnt lgkmcnt(1)
	v_mfma_f32_16x16x32_bf16 v[70:73], v[62:65], v[82:85], v[70:73]
	ds_read_b128 v[82:85], v170 offset:40960
	ds_read_b128 v[148:151], v170 offset:45056
	s_waitcnt lgkmcnt(1)
	v_mfma_f32_16x16x32_bf16 v[82:85], v[50:53], v[82:85], v[70:73]
	s_nop 3
	v_mul_f32_e64 v72, v156, v80
	v_mul_f32_e64 v73, v157, v81
	v_pk_mul_f32 v[70:71], v[98:99], v[78:79]
	s_nop 0
	v_pk_mul_f32 v[84:85], v[124:125], v[84:85]
	v_pk_mul_f32 v[82:83], v[122:123], v[82:83]
	v_mfma_f32_16x16x32_bf16 v[70:73], v[58:61], v[140:143], v[70:73]
	ds_read_b128 v[140:143], v135 offset:53248
	v_mfma_f32_16x16x32_bf16 v[70:73], v[54:57], v[136:139], v[70:73]
	ds_read_b128 v[136:139], v135 offset:49152
	v_mfma_f32_16x16x32_bf16 v[70:73], v[62:65], v[144:147], v[70:73]
	s_waitcnt lgkmcnt(2)
	v_mfma_f32_16x16x32_bf16 v[78:81], v[50:53], v[148:151], v[70:73]
	s_nop 5
	v_mul_f32_e64 v72, v156, v92
	v_mul_f32_e64 v73, v157, v93
	v_pk_mul_f32 v[70:71], v[98:99], v[90:91]
	v_pk_mul_f32 v[80:81], v[124:125], v[80:81]
	v_pk_mul_f32 v[78:79], v[122:123], v[78:79]
	s_waitcnt lgkmcnt(0)
	v_mfma_f32_16x16x32_bf16 v[70:73], v[58:61], v[136:139], v[70:73]
	ds_read_b128 v[90:93], v168 offset:49152
	ds_read_b128 v[136:139], v168 offset:53248
	s_waitcnt lgkmcnt(1)
	v_mfma_f32_16x16x32_bf16 v[70:73], v[54:57], v[90:93], v[70:73]
	ds_read_b128 v[90:93], v169 offset:49152
	ds_read_b128 v[144:147], v169 offset:53248
	s_waitcnt lgkmcnt(1)
	v_mfma_f32_16x16x32_bf16 v[70:73], v[62:65], v[90:93], v[70:73]
	ds_read_b128 v[90:93], v170 offset:49152
	ds_read_b128 v[148:151], v170 offset:53248
	s_waitcnt lgkmcnt(1)
	v_mfma_f32_16x16x32_bf16 v[90:93], v[50:53], v[90:93], v[70:73]
	s_nop 3
	v_mul_f32_e64 v72, v156, v88
	v_mul_f32_e64 v73, v157, v89
	v_pk_mul_f32 v[70:71], v[98:99], v[86:87]
	s_nop 0
	v_pk_mul_f32 v[92:93], v[124:125], v[92:93]
	v_pk_mul_f32 v[90:91], v[122:123], v[90:91]
	v_mfma_f32_16x16x32_bf16 v[70:73], v[58:61], v[140:143], v[70:73]
	v_mfma_f32_16x16x32_bf16 v[70:73], v[54:57], v[136:139], v[70:73]
	v_mfma_f32_16x16x32_bf16 v[70:73], v[62:65], v[144:147], v[70:73]
	s_waitcnt lgkmcnt(0)
	v_mfma_f32_16x16x32_bf16 v[86:89], v[50:53], v[148:151], v[70:73]
	s_nop 5
	ds_read_b128 v[70:73], v135 offset:57344
	ds_read_b128 v[136:139], v168 offset:57344
	ds_read_b128 v[140:143], v135 offset:61440
	s_waitcnt lgkmcnt(2)
	v_mfma_f32_16x16x32_bf16 v[70:73], v[58:61], v[70:73], v[94:97]
	s_nop 2
	ds_read_b128 v[94:97], v169 offset:57344
	ds_read_b128 v[144:147], v168 offset:61440
	v_pk_mul_f32 v[88:89], v[124:125], v[88:89]
	v_pk_mul_f32 v[86:87], v[122:123], v[86:87]
	s_waitcnt lgkmcnt(3)
	v_mfma_f32_16x16x32_bf16 v[70:73], v[54:57], v[136:139], v[70:73]
	ds_read_b128 v[136:139], v170 offset:57344
	ds_read_b128 v[148:151], v169 offset:61440
	ds_read_b128 v[152:155], v170 offset:61440
	s_waitcnt lgkmcnt(4)
	v_mfma_f32_16x16x32_bf16 v[70:73], v[62:65], v[94:97], v[70:73]
	s_waitcnt lgkmcnt(2)
	v_mfma_f32_16x16x32_bf16 v[94:97], v[50:53], v[136:139], v[70:73]
	v_lshl_add_u64 v[136:137], v[158:159], 0, v[100:101]
	v_mfma_f32_16x16x32_bf16 v[70:73], v[58:61], v[140:143], v[66:69]
	v_add_co_u32_e32 v58, vcc, s49, v136
	s_nop 4
	v_pk_mul_f32 v[96:97], v[124:125], v[96:97]
	v_mfma_f32_16x16x32_bf16 v[98:101], v[54:57], v[144:147], v[70:73]
	v_addc_co_u32_e32 v59, vcc, 0, v137, vcc
	v_add_co_u32_e32 v54, vcc, s53, v136
	global_load_dwordx4 v[66:69], v[58:59], off offset:-4096
	s_nop 0
	global_load_dwordx4 v[58:61], v[58:59], off
	v_addc_co_u32_e32 v55, vcc, 0, v137, vcc
	global_load_dwordx4 v[70:73], v[136:137], off
	s_nop 0
	global_load_dwordx4 v[54:57], v[54:55], off
	s_waitcnt lgkmcnt(1)
	v_mfma_f32_16x16x32_bf16 v[142:145], v[62:65], v[148:151], v[98:101]
	v_mul_f32_e64 v94, v122, v94
	v_mul_f32_e64 v95, v123, v95
	v_add_u32_e32 v62, s46, v1
	v_lshl_add_u32 v139, v62, 8, s51
	v_lshlrev_b32_e32 v62, 2, v113
	v_lshl_add_u32 v137, v118, 3, v113
	v_and_b32_e32 v119, 12, v62
	v_lshlrev_b32_e32 v62, 3, v126
	v_lshlrev_b32_e32 v63, 2, v1
	v_and_b32_e32 v62, 8, v62
	v_add_u32_e32 v64, 4, v137
	v_and_b32_e32 v136, 12, v63
	v_bfe_u32 v138, v1, 2, 2
	v_ashrrev_i32_e32 v135, 1, v126
	v_add_u32_e32 v140, s48, v62
	v_bfe_u32 v151, v64, 2, 2
	v_bfe_u32 v141, v137, 2, 2
	v_bitop3_b32 v63, v136, v118, v138 bitop3:0x36
	v_lshl_add_u32 v156, v64, 8, v140
	v_bitop3_b32 v100, v151, v135, v119 bitop3:0x36
	v_bitop3_b32 v62, v141, v135, v119 bitop3:0x36
	v_lshl_add_u32 v63, v63, 4, v139
	v_lshl_add_u32 v150, v137, 8, v140
	v_lshl_add_u32 v100, v100, 4, v156
	v_lshl_add_u32 v157, v62, 4, v150
	ds_read_b128 v[62:65], v63
	ds_read_b64_tr_b16 v[98:99], v157
	ds_read_b64_tr_b16 v[100:101], v100
	v_add_u32_e32 v170, 2, v135
	s_waitcnt lgkmcnt(3)
	v_mfma_f32_16x16x32_bf16 v[50:53], v[50:53], v[152:155], v[142:145]
	v_add_u32_e32 v171, 4, v135
	v_add_u32_e32 v200, 6, v135
	v_add_u32_e32 v201, 8, v135
	ds_read_b64_tr_b16 v[142:143], v157 offset:24576
	s_waitcnt lgkmcnt(1)
	v_mfma_f32_16x16x32_bf16 v[98:101], v[62:65], v[98:101], v[102:105]
	v_add_u32_e32 v202, 10, v135
	v_add_u32_e32 v203, 12, v135
	v_add_u32_e32 v204, 14, v135
	v_bitop3_b32 v102, v141, v170, v119 bitop3:0x36
	v_lshl_add_u32 v146, v102, 4, v150
	ds_read_b64_tr_b16 v[102:103], v146
	v_bitop3_b32 v104, v151, v170, v119 bitop3:0x36
	v_lshl_add_u32 v104, v104, 4, v156
	v_bitop3_b32 v105, v141, v171, v119 bitop3:0x36
	v_lshl_add_u32 v160, v105, 4, v150
	ds_read_b64_tr_b16 v[104:105], v104
	ds_read_b64_tr_b16 v[144:145], v160
	ds_read_b64_tr_b16 v[148:149], v160 offset:8192
	ds_read_b64_tr_b16 v[152:153], v160 offset:16384
	ds_read_b64_tr_b16 v[154:155], v146 offset:8192
	ds_read_b64_tr_b16 v[158:159], v146 offset:16384
	ds_read_b64_tr_b16 v[162:163], v146 offset:24576
	s_waitcnt lgkmcnt(6)
; #define LAS __attribute__((address_space(3)))
; __device__ __forceinline__ s16x4 tr_read(const LAS unsigned char* p) { return __builtin_amdgcn_ds_read_tr16_b64_v4i16((LAS s16x4*)p); }
; __device__ __forceinline__ bf16x8 cat8(s16x4 a, s16x4 b) { return (bf16x8){a[0], a[1], a[2], a[3], b[0], b[1], b[2], b[3]}; }
; __device__ __forceinline__ f32x4 mfma16(bf16x8 a, bf16x8 b, f32x4 c) { return __builtin_amdgcn_mfma_f32_16x16x32_bf16(a, b, c, 0, 0, 0); }
; __device__ __forceinline__ void ret_phase(const Params& P, LAS unsigned char* lds, int tid, int lane, int wave, int bid, int G) {
;     ...
; #pragma unroll
;         for (int ks = 0; ks < 4; ++ks) {
;             const bf16x8 pa = *(const LAS bf16x8*)(Pt + off256(w16 + l15, 4 * ks + g));
;             const unsigned r0 = 32 * ks + 8 * g + q4, r1 = r0 + 4;
; #pragma unroll
;             for (int t = 0; t < 8; ++t) { const unsigned ch = 2 * t + (p >> 1);
;                 const bf16x8 vb = cat8(tr_read(Vt + off256(r0, ch) + 8 * (p & 1)), tr_read(Vt + off256(r1, ch) + 8 * (p & 1)));
;                 o[t] = mfma16(pa, vb, o[t]); }
;         }
	v_mfma_f32_16x16x32_bf16 v[74:77], v[62:65], v[102:105], v[74:77]
	v_bitop3_b32 v102, v151, v171, v119 bitop3:0x36
	v_lshl_add_u32 v102, v102, 4, v156
	ds_read_b64_tr_b16 v[146:147], v102
	v_bitop3_b32 v102, v141, v200, v119 bitop3:0x36
	v_bitop3_b32 v104, v151, v200, v119 bitop3:0x36
	v_lshl_add_u32 v190, v102, 4, v150
	v_lshl_add_u32 v104, v104, 4, v156
	ds_read_b64_tr_b16 v[102:103], v190
	ds_read_b64_tr_b16 v[164:165], v190 offset:8192
	ds_read_b64_tr_b16 v[168:169], v160 offset:24576
	s_waitcnt lgkmcnt(3)
	v_mfma_f32_16x16x32_bf16 v[82:85], v[62:65], v[144:147], v[82:85]
	ds_read_b64_tr_b16 v[104:105], v104
	v_bitop3_b32 v144, v141, v201, v119 bitop3:0x36
	v_lshl_add_u32 v160, v144, 4, v150
	v_bitop3_b32 v144, v151, v201, v119 bitop3:0x36
	v_lshl_add_u32 v144, v144, 4, v156
	ds_read_b64_tr_b16 v[146:147], v144
	ds_read_b64_tr_b16 v[144:145], v160
	ds_read_b64_tr_b16 v[172:173], v190 offset:24576
	s_waitcnt lgkmcnt(3)
	v_mfma_f32_16x16x32_bf16 v[78:81], v[62:65], v[102:105], v[78:81]
	v_bitop3_b32 v104, v141, v202, v119 bitop3:0x36
	v_lshl_add_u32 v104, v104, 4, v150
	v_bitop3_b32 v105, v151, v202, v119 bitop3:0x36
	ds_read_b64_tr_b16 v[102:103], v160 offset:24576
	s_waitcnt lgkmcnt(2)
	v_mfma_f32_16x16x32_bf16 v[90:93], v[62:65], v[144:147], v[90:93]
	ds_read_b64_tr_b16 v[144:145], v104
	v_lshl_add_u32 v105, v105, 4, v156
	v_bitop3_b32 v146, v141, v203, v119 bitop3:0x36
	v_lshl_add_u32 v161, v146, 4, v150
	ds_read_b64_tr_b16 v[146:147], v105
	ds_read_b64_tr_b16 v[174:175], v161
	ds_read_b64_tr_b16 v[178:179], v161 offset:8192
	ds_read_b64_tr_b16 v[182:183], v161 offset:16384
	ds_read_b64_tr_b16 v[184:185], v104 offset:8192
	ds_read_b64_tr_b16 v[188:189], v104 offset:16384
	ds_read_b64_tr_b16 v[192:193], v104 offset:24576
	v_bitop3_b32 v104, v151, v203, v119 bitop3:0x36
	v_lshl_add_u32 v104, v104, 4, v156
	ds_read_b64_tr_b16 v[176:177], v104
	v_bitop3_b32 v105, v151, v204, v119 bitop3:0x36
	v_bitop3_b32 v104, v141, v204, v119 bitop3:0x36
	v_lshl_add_u32 v105, v105, 4, v156
	s_waitcnt lgkmcnt(7)
	v_mfma_f32_16x16x32_bf16 v[86:89], v[62:65], v[144:147], v[86:89]
	v_lshl_add_u32 v104, v104, 4, v150
	ds_read_b64_tr_b16 v[146:147], v105
	ds_read_b64_tr_b16 v[144:145], v104
	ds_read_b64_tr_b16 v[194:195], v104 offset:8192
	ds_read_b64_tr_b16 v[198:199], v161 offset:24576
	v_pk_mul_f32 v[52:53], v[124:125], v[52:53]
	v_pk_mul_f32 v[50:51], v[122:123], v[50:51]
	s_waitcnt lgkmcnt(4)
	v_mfma_f32_16x16x32_bf16 v[94:97], v[62:65], v[174:177], v[94:97]
	ds_read_b64_tr_b16 v[122:123], v104 offset:24576
	v_add_u32_e32 v105, 36, v137
	v_bfe_u32 v124, v105, 2, 2
	s_waitcnt lgkmcnt(3)
	v_mfma_f32_16x16x32_bf16 v[50:53], v[62:65], v[144:147], v[50:53]
	v_add_u32_e32 v62, 4, v118
	v_bitop3_b32 v62, v136, v62, v138 bitop3:0x36
	v_lshl_add_u32 v62, v62, 4, v139
	ds_read_b128 v[62:65], v62
	v_lshl_add_u32 v105, v105, 8, v140
	v_bitop3_b32 v125, v124, v135, v119 bitop3:0x36
	v_lshl_add_u32 v125, v125, 4, v105
	ds_read_b64_tr_b16 v[146:147], v125
	ds_read_b64_tr_b16 v[144:145], v157 offset:8192
	ds_read_b64_tr_b16 v[174:175], v157 offset:16384
	v_bitop3_b32 v125, v124, v170, v119 bitop3:0x36
	v_lshl_add_u32 v125, v125, 4, v105
	ds_read_b64_tr_b16 v[156:157], v125
	v_bitop3_b32 v125, v124, v171, v119 bitop3:0x36
	s_waitcnt lgkmcnt(2)
	v_mfma_f32_16x16x32_bf16 v[98:101], v[62:65], v[144:147], v[98:101]
	v_lshl_add_u32 v125, v125, 4, v105
	v_bitop3_b32 v141, v124, v200, v119 bitop3:0x36
	v_bitop3_b32 v144, v124, v201, v119 bitop3:0x36
	v_lshl_add_u32 v141, v141, 4, v105
	v_lshl_add_u32 v144, v144, 4, v105
	ds_read_b64_tr_b16 v[150:151], v125
	ds_read_b64_tr_b16 v[166:167], v141
	ds_read_b64_tr_b16 v[146:147], v144
	v_bitop3_b32 v125, v124, v202, v119 bitop3:0x36
	v_lshl_add_u32 v125, v125, 4, v105
	s_waitcnt lgkmcnt(2)
	v_mfma_f32_16x16x32_bf16 v[82:85], v[62:65], v[148:151], v[82:85]
	ds_read_b64_tr_b16 v[144:145], v160 offset:8192
	ds_read_b64_tr_b16 v[148:149], v160 offset:16384
	ds_read_b64_tr_b16 v[186:187], v125
	v_bitop3_b32 v125, v124, v203, v119 bitop3:0x36
	v_lshl_add_u32 v125, v125, 4, v105
	v_bitop3_b32 v124, v124, v204, v119 bitop3:0x36
	v_lshl_add_u32 v105, v124, 4, v105
	ds_read_b64_tr_b16 v[180:181], v125
	ds_read_b64_tr_b16 v[196:197], v105
	v_add_u32_e32 v105, 0x44, v137
	v_mfma_f32_16x16x32_bf16 v[74:77], v[62:65], v[154:157], v[74:77]
	v_bfe_u32 v124, v105, 2, 2
	v_lshl_add_u32 v105, v105, 8, v140
	v_bitop3_b32 v125, v124, v135, v119 bitop3:0x36
	s_waitcnt lgkmcnt(6)
	v_mfma_f32_16x16x32_bf16 v[78:81], v[62:65], v[164:167], v[78:81]
	v_lshl_add_u32 v125, v125, 4, v105
	ds_read_b64_tr_b16 v[176:177], v125
	v_bitop3_b32 v125, v124, v170, v119 bitop3:0x36
	s_waitcnt lgkmcnt(5)
	v_mfma_f32_16x16x32_bf16 v[90:93], v[62:65], v[144:147], v[90:93]
	v_lshl_add_u32 v125, v125, 4, v105
	ds_read_b64_tr_b16 v[160:161], v125
	v_bitop3_b32 v125, v124, v171, v119 bitop3:0x36
	s_waitcnt lgkmcnt(4)
	v_mfma_f32_16x16x32_bf16 v[86:89], v[62:65], v[184:187], v[86:89]
	v_bitop3_b32 v144, v124, v201, v119 bitop3:0x36
	v_lshl_add_u32 v125, v125, 4, v105
	v_bitop3_b32 v141, v124, v200, v119 bitop3:0x36
	s_waitcnt lgkmcnt(3)
	v_mfma_f32_16x16x32_bf16 v[94:97], v[62:65], v[178:181], v[94:97]
	v_lshl_add_u32 v144, v144, 4, v105
	v_lshl_add_u32 v141, v141, 4, v105
	s_waitcnt lgkmcnt(2)
	v_mfma_f32_16x16x32_bf16 v[50:53], v[62:65], v[194:197], v[50:53]
	v_add_u32_e32 v62, 8, v118
	v_bitop3_b32 v62, v136, v62, v138 bitop3:0x36
	v_lshl_add_u32 v62, v62, 4, v139
	ds_read_b128 v[62:65], v62
	ds_read_b64_tr_b16 v[154:155], v125
	ds_read_b64_tr_b16 v[146:147], v141
	ds_read_b64_tr_b16 v[150:151], v144
	ds_read_b64_tr_b16 v[144:145], v190 offset:16384
	s_waitcnt lgkmcnt(0)
; #define LAS __attribute__((address_space(3)))
; __device__ __forceinline__ s16x4 tr_read(const LAS unsigned char* p) { return __builtin_amdgcn_ds_read_tr16_b64_v4i16((LAS s16x4*)p); }
; __device__ __forceinline__ bf16x8 cat8(s16x4 a, s16x4 b) { return (bf16x8){a[0], a[1], a[2], a[3], b[0], b[1], b[2], b[3]}; }
; __device__ __forceinline__ f32x4 mfma16(bf16x8 a, bf16x8 b, f32x4 c) { return __builtin_amdgcn_mfma_f32_16x16x32_bf16(a, b, c, 0, 0, 0); }
; #define LBAR() asm volatile("s_waitcnt lgkmcnt(0)\n\ts_barrier" ::: "memory")
; #define OPQ_ALL() do { asm volatile("" : "+v"(g), "+v"(l15), "+v"(q4), "+v"(p)); } while (0)
; __device__ __forceinline__ void ret_phase(const Params& P, LAS unsigned char* lds, int tid, int lane, int wave, int bid, int G) {
;     ...
; #pragma unroll
;         for (int ks = 0; ks < 4; ++ks) {
;             const bf16x8 pa = *(const LAS bf16x8*)(Pt + off256(w16 + l15, 4 * ks + g));
;             const unsigned r0 = 32 * ks + 8 * g + q4, r1 = r0 + 4;
; #pragma unroll
;             for (int t = 0; t < 8; ++t) { const unsigned ch = 2 * t + (p >> 1);
;                 const bf16x8 vb = cat8(tr_read(Vt + off256(r0, ch) + 8 * (p & 1)), tr_read(Vt + off256(r1, ch) + 8 * (p & 1)));
;                 o[t] = mfma16(pa, vb, o[t]); }
;         }
;         OPQ_ALL();
;         float rs[4];
; #pragma unroll
;         for (int i = 0; i < 4; ++i) { float ss = 0.f;
; #pragma unroll
;             for (int t = 0; t < 8; ++t) ss += o[t][i] * o[t][i];
;             ss += __shfl_xor(ss, 1); ss += __shfl_xor(ss, 2); ss += __shfl_xor(ss, 4); ss += __shfl_xor(ss, 8);
;             rs[i] = rsqrtf(ss * (1.f / 128.f) + EPS); }
;         LBAR();
	v_mfma_f32_16x16x32_bf16 v[78:81], v[62:65], v[144:147], v[78:81]
	v_mfma_f32_16x16x32_bf16 v[146:149], v[62:65], v[148:151], v[90:93]
	s_nop 2
	v_bitop3_b32 v90, v124, v202, v119 bitop3:0x36
	v_lshl_add_u32 v90, v90, 4, v105
	ds_read_b64_tr_b16 v[190:191], v90
	v_bitop3_b32 v90, v124, v203, v119 bitop3:0x36
	v_bitop3_b32 v91, v124, v204, v119 bitop3:0x36
	v_lshl_add_u32 v90, v90, 4, v105
	v_lshl_add_u32 v91, v91, 4, v105
	v_mfma_f32_16x16x32_bf16 v[82:85], v[62:65], v[152:155], v[82:85]
	ds_read_b64_tr_b16 v[184:185], v90
	ds_read_b64_tr_b16 v[90:91], v91
	s_waitcnt lgkmcnt(2)
	v_mfma_f32_16x16x32_bf16 v[150:153], v[62:65], v[188:191], v[86:89]
	s_nop 2
	ds_read_b64_tr_b16 v[88:89], v104 offset:16384
	v_mfma_f32_16x16x32_bf16 v[98:101], v[62:65], v[174:177], v[98:101]
	v_mfma_f32_16x16x32_bf16 v[74:77], v[62:65], v[158:161], v[74:77]
	s_waitcnt lgkmcnt(2)
	v_mfma_f32_16x16x32_bf16 v[154:157], v[62:65], v[182:185], v[94:97]
	s_waitcnt lgkmcnt(0)
	v_mfma_f32_16x16x32_bf16 v[50:53], v[62:65], v[88:91], v[50:53]
	v_add_u32_e32 v62, 12, v118
	v_bitop3_b32 v62, v136, v62, v138 bitop3:0x36
	v_lshl_add_u32 v62, v62, 4, v139
	ds_read_b128 v[158:161], v62
	v_add_u32_e32 v62, 0x64, v137
	v_bfe_u32 v63, v62, 2, 2
	v_lshl_add_u32 v62, v62, 8, v140
	v_bitop3_b32 v64, v63, v135, v119 bitop3:0x36
	v_lshl_add_u32 v64, v64, 4, v62
	ds_read_b64_tr_b16 v[144:145], v64
	v_bitop3_b32 v64, v63, v170, v119 bitop3:0x36
	v_lshl_add_u32 v64, v64, 4, v62
	ds_read_b64_tr_b16 v[164:165], v64
	v_bitop3_b32 v64, v63, v171, v119 bitop3:0x36
	v_lshl_add_u32 v64, v64, 4, v62
	v_bitop3_b32 v65, v63, v200, v119 bitop3:0x36
	v_bitop3_b32 v86, v63, v201, v119 bitop3:0x36
	v_lshl_add_u32 v65, v65, 4, v62
	v_lshl_add_u32 v86, v86, 4, v62
	ds_read_b64_tr_b16 v[170:171], v64
	ds_read_b64_tr_b16 v[174:175], v65
	ds_read_b64_tr_b16 v[104:105], v86
	v_bitop3_b32 v64, v63, v202, v119 bitop3:0x36
	v_lshl_add_u32 v64, v64, 4, v62
	ds_read_b64_tr_b16 v[194:195], v64
	v_bitop3_b32 v64, v63, v203, v119 bitop3:0x36
	v_lshl_add_u32 v64, v64, 4, v62
	v_bitop3_b32 v63, v63, v204, v119 bitop3:0x36
	v_lshl_add_u32 v62, v63, 4, v62
	ds_read_b64_tr_b16 v[200:201], v64
	ds_read_b64_tr_b16 v[124:125], v62
	s_waitcnt lgkmcnt(7)
	v_mfma_f32_16x16x32_bf16 v[94:97], v[158:161], v[142:145], v[98:101]
	v_xor_b32_e32 v140, 2, v134
	s_waitcnt lgkmcnt(0)
	s_waitcnt lgkmcnt(5)
	v_mfma_f32_16x16x32_bf16 v[86:89], v[158:161], v[168:171], v[82:85]
	v_and_b32_e32 v99, 64, v134
	v_xor_b32_e32 v98, 1, v134
	s_waitcnt lgkmcnt(4)
	v_mfma_f32_16x16x32_bf16 v[82:85], v[158:161], v[172:175], v[78:81]
	v_add_u32_e32 v119, 64, v99
	v_cmp_lt_i32_e32 vcc, v98, v119
	v_mfma_f32_16x16x32_bf16 v[90:93], v[158:161], v[162:165], v[74:77]
	s_nop 0
	v_cndmask_b32_e32 v98, v134, v98, vcc
	v_lshlrev_b32_e32 v135, 2, v98
	v_mov_b32_e32 v98, v86
	s_waitcnt lgkmcnt(3)
	v_mfma_f32_16x16x32_bf16 v[78:81], v[158:161], v[102:105], v[146:149]
	v_mov_b32_e32 v99, v82
	v_mov_b32_e32 v104, v87
	v_mov_b32_e32 v105, v83
	s_waitcnt lgkmcnt(2)
	v_mfma_f32_16x16x32_bf16 v[74:77], v[158:161], v[192:195], v[150:153]
	v_mul_f32_e64 v98, v98, v98
	v_mul_f32_e64 v99, v99, v99
	v_pk_mul_f32 v[104:105], v[104:105], v[104:105]
	v_mov_b32_e32 v100, v78
	s_waitcnt lgkmcnt(1)
	v_mfma_f32_16x16x32_bf16 v[62:65], v[158:161], v[198:201], v[154:157]
	v_mov_b32_e32 v138, v104
	s_nop 0
	v_mov_b32_e32 v101, v74
	v_mov_b32_e32 v139, v98
	s_waitcnt lgkmcnt(0)
	v_mfma_f32_16x16x32_bf16 v[50:53], v[158:161], v[122:125], v[50:53]
	v_mul_f32_e64 v122, v90, v90
	v_mul_f32_e64 v123, v91, v91
	v_mov_b32_e32 v124, v79
	v_pk_fma_f32 v[122:123], v[94:95], v[94:95], v[122:123]
	v_mov_b32_e32 v125, v75
	v_pk_mul_f32 v[100:101], v[100:101], v[100:101]
	v_pk_mul_f32 v[124:125], v[124:125], v[124:125]
	v_pk_add_f32 v[122:123], v[122:123], v[138:139] op_sel:[1,0] op_sel_hi:[0,1]
	v_mov_b32_e32 v98, v105
	v_mov_b32_e32 v102, v62
	v_mov_b32_e32 v103, v50
	v_mov_b32_e32 v136, v63
	v_mov_b32_e32 v137, v51
	v_pk_add_f32 v[98:99], v[122:123], v[98:99]
	v_mov_b32_e32 v104, v124
	v_mov_b32_e32 v105, v100
	v_pk_mul_f32 v[102:103], v[102:103], v[102:103]
	v_pk_mul_f32 v[136:137], v[136:137], v[136:137]
	v_pk_add_f32 v[98:99], v[98:99], v[104:105]
	v_mov_b32_e32 v100, v125
	v_pk_add_f32 v[98:99], v[98:99], v[100:101]
	v_mov_b32_e32 v100, v136
	v_mov_b32_e32 v101, v102
	v_pk_add_f32 v[98:99], v[98:99], v[100:101]
	v_mov_b32_e32 v102, v137
	v_pk_add_f32 v[98:99], v[98:99], v[102:103]
	s_nop 1
	v_mov_b32_dpp v101, v99 quad_perm:[1,0,3,2] row_mask:0xf bank_mask:0xf
	v_mov_b32_dpp v100, v98 quad_perm:[1,0,3,2] row_mask:0xf bank_mask:0xf
	v_cmp_lt_i32_e32 vcc, v140, v119
	v_mov_b32_e32 v122, v88
	v_mov_b32_e32 v123, v84
	v_cndmask_b32_e32 v102, v134, v140, vcc
	v_lshlrev_b32_e32 v146, 2, v102
	s_waitcnt lgkmcnt(0)
	v_pk_add_f32 v[98:99], v[98:99], v[100:101]
	s_nop 1
	v_mov_b32_dpp v101, v99 quad_perm:[2,3,0,1] row_mask:0xf bank_mask:0xf
	v_mov_b32_dpp v100, v98 quad_perm:[2,3,0,1] row_mask:0xf bank_mask:0xf
	v_xor_b32_e32 v102, 4, v134
	v_cmp_lt_i32_e32 vcc, v102, v119
	v_mov_b32_e32 v138, v89
	v_mov_b32_e32 v139, v85
	v_cndmask_b32_e32 v102, v134, v102, vcc
	v_lshlrev_b32_e32 v147, 2, v102
	s_waitcnt lgkmcnt(0)
	v_pk_add_f32 v[98:99], v[98:99], v[100:101]
	s_nop 1
	v_mov_b32_dpp v101, v99 row_half_mirror row_mask:0xf bank_mask:0xf
	v_mov_b32_dpp v100, v98 row_half_mirror row_mask:0xf bank_mask:0xf
	v_xor_b32_e32 v102, 8, v134
	v_cmp_lt_i32_e32 vcc, v102, v119
	v_pk_mul_f32 v[122:123], v[122:123], v[122:123]
	v_pk_mul_f32 v[138:139], v[138:139], v[138:139]
	s_waitcnt lgkmcnt(0)
; __device__ __forceinline__ unsigned cvt_pk_bf16(float lo, float hi) { unsigned r; asm volatile("v_cvt_pk_bf16_f32 %0, %1, %2" : "=v"(r) : "v"(lo), "v"(hi)); return r; }
; #define LAS __attribute__((address_space(3)))
; #define LBAR() asm volatile("s_waitcnt lgkmcnt(0)\n\ts_barrier" ::: "memory")
; __device__ __forceinline__ void ret_phase(const Params& P, LAS unsigned char* lds, int tid, int lane, int wave, int bid, int G) {
;     ...
;         float rs[4];
; #pragma unroll
;         for (int i = 0; i < 4; ++i) { float ss = 0.f;
; #pragma unroll
;             for (int t = 0; t < 8; ++t) ss += o[t][i] * o[t][i];
;             ss += __shfl_xor(ss, 1); ss += __shfl_xor(ss, 2); ss += __shfl_xor(ss, 4); ss += __shfl_xor(ss, 8);
;             rs[i] = rsqrtf(ss * (1.f / 128.f) + EPS); }
;         LBAR();
; #pragma unroll
;         for (int t = 0; t < 8; ++t) { const int dv = 16 * t + l15; const float gn = P.rgain[h * 128 + dv];
; #pragma unroll
;             for (int i = 0; i < 4; ++i) { const int n = w16 + 4 * g + i; const unsigned wv = cvt_pk_bf16(o[t][i] * rs[i] * gn, 0.f);
;                 *(LAS unsigned short*)(Pt + off256(n, dv >> 3) + 2 * (dv & 7)) = (unsigned short)(wv & 0xffffu); } }
	v_pk_add_f32 v[100:101], v[98:99], v[100:101]
	v_lshl_add_u32 v98, s57, 7, v1
	v_ashrrev_i32_e32 v99, 31, v98
	v_lshl_add_u64 v[98:99], v[98:99], 2, s[62:63]
	v_mov_b32_e32 v148, v205
	v_cndmask_b32_e32 v102, v134, v102, vcc
	v_lshlrev_b32_e32 v119, 2, v102
	v_pk_mul_f32 v[102:103], v[92:93], v[92:93]
	v_mov_b32_e32 v124, v80
	v_pk_fma_f32 v[102:103], v[96:97], v[96:97], v[102:103]
	v_mov_b32_e32 v125, v76
	v_mov_b32_e32 v140, v81
	v_mov_b32_e32 v141, v77
	v_mov_b32_e32 v144, v138
	v_mov_b32_e32 v145, v122
	v_pk_mul_f32 v[124:125], v[124:125], v[124:125]
	v_pk_mul_f32 v[140:141], v[140:141], v[140:141]
	v_pk_add_f32 v[102:103], v[102:103], v[144:145] op_sel:[1,0] op_sel_hi:[0,1]
	v_mov_b32_e32 v122, v139
	v_mov_b32_e32 v136, v64
	v_mov_b32_e32 v137, v52
	v_mov_b32_e32 v142, v65
	v_mov_b32_e32 v143, v53
	v_pk_add_f32 v[102:103], v[102:103], v[122:123]
	v_mov_b32_e32 v122, v140
	v_mov_b32_e32 v123, v124
	v_pk_mul_f32 v[136:137], v[136:137], v[136:137]
	v_pk_mul_f32 v[142:143], v[142:143], v[142:143]
	v_pk_add_f32 v[102:103], v[102:103], v[122:123]
	v_mov_b32_e32 v124, v141
	v_pk_add_f32 v[102:103], v[102:103], v[124:125]
	v_mov_b32_e32 v122, v142
	v_mov_b32_e32 v123, v136
	v_pk_add_f32 v[102:103], v[102:103], v[122:123]
	v_mov_b32_e32 v136, v143
	v_pk_add_f32 v[102:103], v[102:103], v[136:137]
	s_nop 1
	v_mov_b32_dpp v123, v103 quad_perm:[1,0,3,2] row_mask:0xf bank_mask:0xf
	v_mov_b32_dpp v122, v102 quad_perm:[1,0,3,2] row_mask:0xf bank_mask:0xf
	v_mov_b32_dpp v105, v101 row_mirror row_mask:0xf bank_mask:0xf
	v_mov_b32_dpp v104, v100 row_mirror row_mask:0xf bank_mask:0xf
	s_waitcnt lgkmcnt(2)
	v_pk_add_f32 v[102:103], v[102:103], v[122:123]
	s_nop 1
	v_mov_b32_dpp v123, v103 quad_perm:[2,3,0,1] row_mask:0xf bank_mask:0xf
	v_mov_b32_dpp v122, v102 quad_perm:[2,3,0,1] row_mask:0xf bank_mask:0xf
	s_waitcnt lgkmcnt(2)
	v_pk_add_f32 v[100:101], v[100:101], v[104:105]
	v_mov_b64_e32 v[104:105], s[24:25]
	v_pk_fma_f32 v[100:101], v[100:101], s[20:21], v[104:105] op_sel_hi:[1,0,0]
	s_waitcnt lgkmcnt(0)
	v_pk_add_f32 v[102:103], v[102:103], v[122:123]
	s_nop 1
	v_mov_b32_dpp v123, v103 row_half_mirror row_mask:0xf bank_mask:0xf
	v_mov_b32_dpp v122, v102 row_half_mirror row_mask:0xf bank_mask:0xf
	v_mul_f32_e32 v124, 0x4b800000, v101
	v_cmp_gt_f32_e32 vcc, s54, v101
	v_cmp_gt_f32_e64 s[0:1], s54, v100
	s_nop 0
	v_cndmask_b32_e32 v101, v101, v124, vcc
	v_rsq_f32_e32 v124, v101
	v_mul_f32_e32 v101, 0x4b800000, v100
	v_cndmask_b32_e64 v100, v100, v101, s[0:1]
	v_rsq_f32_e32 v125, v100
	s_waitcnt lgkmcnt(0)
	v_pk_add_f32 v[100:101], v[102:103], v[122:123]
	s_nop 1
	v_mov_b32_dpp v103, v101 row_mirror row_mask:0xf bank_mask:0xf
	v_mov_b32_dpp v102, v100 row_mirror row_mask:0xf bank_mask:0xf
	v_mul_f32_e32 v119, 0x45800000, v124
	v_cndmask_b32_e32 v119, v124, v119, vcc
	v_mul_f32_e32 v122, 0x45800000, v125
	v_mul_f32_e32 v94, v94, v119
	s_waitcnt lgkmcnt(0)
	v_pk_add_f32 v[100:101], v[100:101], v[102:103]
	v_mul_f32_e32 v90, v90, v119
	v_pk_fma_f32 v[100:101], v[100:101], s[20:21], v[104:105] op_sel_hi:[1,0,0]
	v_lshlrev_b32_e32 v105, 1, v1
	v_mul_f32_e32 v102, 0x4b800000, v101
	v_cmp_gt_f32_e32 vcc, s54, v101
	v_cmp_gt_f32_e64 s[4:5], s54, v100
	v_and_b32_e32 v105, 14, v105
	v_cndmask_b32_e32 v101, v101, v102, vcc
	v_mul_f32_e32 v102, 0x4b800000, v100
	v_rsq_f32_e32 v101, v101
	v_cndmask_b32_e64 v100, v100, v102, s[4:5]
	v_rsq_f32_e32 v100, v100
	v_cndmask_b32_e64 v102, v125, v122, s[0:1]
	v_mul_f32_e32 v103, 0x45800000, v101
	v_cndmask_b32_e32 v101, v101, v103, vcc
	v_mul_f32_e32 v103, 0x45800000, v100
	v_lshrrev_b32_e32 v122, 3, v1
	v_cndmask_b32_e64 v100, v100, v103, s[4:5]
	v_lshlrev_b32_e32 v103, 2, v118
	v_bitop3_b32 v124, v118, v122, 3 bitop3:0x6c
	s_waitcnt vmcnt(0)
	v_mul_f32_e32 v94, v94, v148
	v_add_lshl_u32 v123, v103, s46, 8
	v_lshl_add_u32 v124, v124, 4, s51
	v_and_b32_e32 v104, 3, v118
	v_cvt_pk_bf16_f32 v94, v94, v115
	v_add3_u32 v124, v124, v123, v105
	ds_write_b16 v124, v94
	v_mul_f32_e32 v94, v95, v102
	v_bitop3_b32 v95, v104, v122, 4 bitop3:0x36
	v_mul_f32_e32 v94, v148, v94
	v_lshl_add_u32 v95, v95, 4, s51
	v_cvt_pk_bf16_f32 v94, v94, v115
	v_add3_u32 v95, v95, v123, v105
	ds_write_b16 v95, v94 offset:256
	v_mul_f32_e32 v94, v96, v101
	v_bitop3_b32 v95, v104, v122, 8 bitop3:0x36
	v_mul_f32_e32 v94, v148, v94
	v_lshl_add_u32 v95, v95, 4, s51
	v_cvt_pk_bf16_f32 v94, v94, v115
	v_add3_u32 v95, v95, v123, v105
	ds_write_b16 v95, v94 offset:512
	v_mul_f32_e32 v94, v97, v100
	v_mul_f32_e32 v94, v148, v94
	v_cvt_pk_bf16_f32 v94, v94, v115
	v_mov_b32_e32 v95, v206
	v_bitop3_b32 v96, v104, v122, 12 bitop3:0x36
	v_lshl_add_u32 v96, v96, 4, s51
	v_add3_u32 v96, v96, v123, v105
	ds_write_b16 v96, v94 offset:768
	v_add_u32_e32 v94, 16, v1
	v_lshrrev_b32_e32 v94, 3, v94
	v_bitop3_b32 v96, v94, v118, 3 bitop3:0x78
	v_lshl_add_u32 v96, v96, 4, s51
	v_add3_u32 v96, v96, v123, v105
	v_mul_f32_e32 v86, v86, v119
	v_mul_f32_e32 v82, v82, v119
	v_mul_f32_e32 v78, v78, v119
	v_mul_f32_e32 v74, v74, v119
	v_mul_f32_e32 v62, v62, v119
	v_mul_f32_e32 v50, v50, v119
	s_waitcnt vmcnt(0)
	v_mul_f32_e32 v90, v90, v95
	v_cvt_pk_bf16_f32 v90, v90, v115
	ds_write_b16 v96, v90
	v_mul_f32_e32 v90, v91, v102
	v_bitop3_b32 v91, v104, v94, 4 bitop3:0x36
	v_mul_f32_e32 v90, v90, v95
	v_lshl_add_u32 v91, v91, 4, s51
	v_cvt_pk_bf16_f32 v90, v90, v115
	v_add3_u32 v91, v91, v123, v105
	ds_write_b16 v91, v90 offset:256
	v_mul_f32_e32 v90, v92, v101
	v_bitop3_b32 v91, v104, v94, 8 bitop3:0x36
	v_mul_f32_e32 v90, v90, v95
	v_lshl_add_u32 v91, v91, 4, s51
	v_cvt_pk_bf16_f32 v90, v90, v115
	v_add3_u32 v91, v91, v123, v105
	ds_write_b16 v91, v90 offset:512
	v_mul_f32_e32 v90, v93, v100
	v_mul_f32_e32 v90, v90, v95
	v_cvt_pk_bf16_f32 v90, v90, v115
	v_mov_b32_e32 v91, v207
	v_bitop3_b32 v92, v104, v94, 12 bitop3:0x36
	v_lshl_add_u32 v92, v92, 4, s51
	v_add3_u32 v92, v92, v123, v105
	ds_write_b16 v92, v90 offset:768
	v_add_u32_e32 v90, 32, v1
	v_lshrrev_b32_e32 v90, 3, v90
	v_bitop3_b32 v92, v90, v118, 3 bitop3:0x78
	v_lshl_add_u32 v92, v92, 4, s51
	v_add3_u32 v92, v92, v123, v105
	s_waitcnt vmcnt(0)
; __device__ __forceinline__ unsigned cvt_pk_bf16(float lo, float hi) { unsigned r; asm volatile("v_cvt_pk_bf16_f32 %0, %1, %2" : "=v"(r) : "v"(lo), "v"(hi)); return r; }
; #define LAS __attribute__((address_space(3)))
; __device__ __forceinline__ void ret_phase(const Params& P, LAS unsigned char* lds, int tid, int lane, int wave, int bid, int G) {
;     ...
; #pragma unroll
;         for (int t = 0; t < 8; ++t) { const int dv = 16 * t + l15; const float gn = P.rgain[h * 128 + dv];
; #pragma unroll
;             for (int i = 0; i < 4; ++i) { const int n = w16 + 4 * g + i; const unsigned wv = cvt_pk_bf16(o[t][i] * rs[i] * gn, 0.f);
;                 *(LAS unsigned short*)(Pt + off256(n, dv >> 3) + 2 * (dv & 7)) = (unsigned short)(wv & 0xffffu); } }
	v_mul_f32_e32 v86, v86, v91
	v_cvt_pk_bf16_f32 v86, v86, v115
	ds_write_b16 v92, v86
	v_mul_f32_e32 v86, v87, v102
	v_bitop3_b32 v87, v104, v90, 4 bitop3:0x36
	v_mul_f32_e32 v86, v86, v91
	v_lshl_add_u32 v87, v87, 4, s51
	v_cvt_pk_bf16_f32 v86, v86, v115
	v_add3_u32 v87, v87, v123, v105
	ds_write_b16 v87, v86 offset:256
	v_mul_f32_e32 v86, v88, v101
	v_bitop3_b32 v87, v104, v90, 8 bitop3:0x36
	v_mul_f32_e32 v86, v86, v91
	v_lshl_add_u32 v87, v87, 4, s51
	v_cvt_pk_bf16_f32 v86, v86, v115
	v_add3_u32 v87, v87, v123, v105
	ds_write_b16 v87, v86 offset:512
	v_mul_f32_e32 v86, v89, v100
	v_mul_f32_e32 v86, v86, v91
	v_cvt_pk_bf16_f32 v86, v86, v115
	v_mov_b32_e32 v87, v208
	v_bitop3_b32 v88, v104, v90, 12 bitop3:0x36
	v_lshl_add_u32 v88, v88, 4, s51
	v_add3_u32 v88, v88, v123, v105
	ds_write_b16 v88, v86 offset:768
	v_add_u32_e32 v86, 48, v1
	v_lshrrev_b32_e32 v86, 3, v86
	v_bitop3_b32 v88, v86, v118, 3 bitop3:0x78
	v_lshl_add_u32 v88, v88, 4, s51
	v_add3_u32 v88, v88, v123, v105
	s_waitcnt vmcnt(0)
	v_mul_f32_e32 v82, v82, v87
	v_cvt_pk_bf16_f32 v82, v82, v115
	ds_write_b16 v88, v82
	v_mul_f32_e32 v82, v83, v102
	v_bitop3_b32 v83, v104, v86, 4 bitop3:0x36
	v_mul_f32_e32 v82, v82, v87
	v_lshl_add_u32 v83, v83, 4, s51
	v_cvt_pk_bf16_f32 v82, v82, v115
	v_add3_u32 v83, v83, v123, v105
	ds_write_b16 v83, v82 offset:256
	v_mul_f32_e32 v82, v84, v101
	v_bitop3_b32 v83, v104, v86, 8 bitop3:0x36
	v_mul_f32_e32 v82, v82, v87
	v_lshl_add_u32 v83, v83, 4, s51
	v_cvt_pk_bf16_f32 v82, v82, v115
	v_add3_u32 v83, v83, v123, v105
	ds_write_b16 v83, v82 offset:512
	v_mul_f32_e32 v82, v85, v100
	v_mul_f32_e32 v82, v82, v87
	v_cvt_pk_bf16_f32 v82, v82, v115
	v_mov_b32_e32 v83, v209
	v_bitop3_b32 v84, v104, v86, 12 bitop3:0x36
	v_lshl_add_u32 v84, v84, 4, s51
	v_add3_u32 v84, v84, v123, v105
	ds_write_b16 v84, v82 offset:768
	v_add_u32_e32 v82, 64, v1
	v_lshrrev_b32_e32 v82, 3, v82
	v_bitop3_b32 v84, v82, v118, 3 bitop3:0x78
	v_lshl_add_u32 v84, v84, 4, s51
	v_add3_u32 v84, v84, v123, v105
	s_waitcnt vmcnt(0)
	v_mul_f32_e32 v78, v78, v83
	v_cvt_pk_bf16_f32 v78, v78, v115
	ds_write_b16 v84, v78
	v_mul_f32_e32 v78, v79, v102
	v_bitop3_b32 v79, v104, v82, 4 bitop3:0x36
	v_mul_f32_e32 v78, v78, v83
	v_lshl_add_u32 v79, v79, 4, s51
	v_cvt_pk_bf16_f32 v78, v78, v115
	v_add3_u32 v79, v79, v123, v105
	ds_write_b16 v79, v78 offset:256
	v_mul_f32_e32 v78, v80, v101
	v_bitop3_b32 v79, v104, v82, 8 bitop3:0x36
	v_mul_f32_e32 v78, v78, v83
	v_lshl_add_u32 v79, v79, 4, s51
	v_cvt_pk_bf16_f32 v78, v78, v115
	v_add3_u32 v79, v79, v123, v105
	ds_write_b16 v79, v78 offset:512
	v_mul_f32_e32 v78, v81, v100
	v_mul_f32_e32 v78, v78, v83
	v_cvt_pk_bf16_f32 v78, v78, v115
	v_mov_b32_e32 v79, v210
	v_bitop3_b32 v80, v104, v82, 12 bitop3:0x36
	v_lshl_add_u32 v80, v80, 4, s51
	v_add3_u32 v80, v80, v123, v105
	ds_write_b16 v80, v78 offset:768
	v_add_u32_e32 v78, 0x50, v1
	v_lshrrev_b32_e32 v78, 3, v78
	v_bitop3_b32 v80, v78, v118, 3 bitop3:0x78
	v_lshl_add_u32 v80, v80, 4, s51
	v_add3_u32 v80, v80, v123, v105
	s_waitcnt vmcnt(0)
	v_mul_f32_e32 v74, v74, v79
	v_cvt_pk_bf16_f32 v74, v74, v115
	ds_write_b16 v80, v74
	v_mul_f32_e32 v74, v75, v102
	v_bitop3_b32 v75, v104, v78, 4 bitop3:0x36
	v_mul_f32_e32 v74, v74, v79
	v_lshl_add_u32 v75, v75, 4, s51
	v_cvt_pk_bf16_f32 v74, v74, v115
	v_add3_u32 v75, v75, v123, v105
	ds_write_b16 v75, v74 offset:256
	v_mul_f32_e32 v74, v76, v101
	v_bitop3_b32 v75, v104, v78, 8 bitop3:0x36
	v_mul_f32_e32 v74, v74, v79
	v_lshl_add_u32 v75, v75, 4, s51
	v_cvt_pk_bf16_f32 v74, v74, v115
	v_add3_u32 v75, v75, v123, v105
	ds_write_b16 v75, v74 offset:512
	v_mul_f32_e32 v74, v77, v100
	v_mul_f32_e32 v74, v74, v79
	v_cvt_pk_bf16_f32 v74, v74, v115
	v_mov_b32_e32 v75, v211
	v_bitop3_b32 v76, v104, v78, 12 bitop3:0x36
	v_lshl_add_u32 v76, v76, 4, s51
	v_add3_u32 v76, v76, v123, v105
	ds_write_b16 v76, v74 offset:768
	v_add_u32_e32 v74, 0x60, v1
	v_lshrrev_b32_e32 v74, 3, v74
	v_bitop3_b32 v76, v74, v118, 3 bitop3:0x78
	v_lshl_add_u32 v76, v76, 4, s51
	v_add3_u32 v76, v76, v123, v105
	v_and_b32_e32 v78, 12, v103
	s_waitcnt vmcnt(0)
	v_mul_f32_e32 v62, v62, v75
	v_cvt_pk_bf16_f32 v62, v62, v115
	ds_write_b16 v76, v62
	v_mul_f32_e32 v62, v63, v102
	v_bitop3_b32 v63, v104, v74, 4 bitop3:0x36
	v_mul_f32_e32 v62, v62, v75
	v_lshl_add_u32 v63, v63, 4, s51
	v_cvt_pk_bf16_f32 v62, v62, v115
	v_add3_u32 v63, v63, v123, v105
	ds_write_b16 v63, v62 offset:256
	v_mul_f32_e32 v62, v64, v101
	v_bitop3_b32 v63, v104, v74, 8 bitop3:0x36
	v_mul_f32_e32 v62, v62, v75
	v_lshl_add_u32 v63, v63, 4, s51
	v_cvt_pk_bf16_f32 v62, v62, v115
	v_add3_u32 v63, v63, v123, v105
	ds_write_b16 v63, v62 offset:512
	v_mul_f32_e32 v62, v65, v100
	v_mul_f32_e32 v62, v62, v75
	v_cvt_pk_bf16_f32 v62, v62, v115
	v_mov_b32_e32 v63, v212
	v_bitop3_b32 v64, v104, v74, 12 bitop3:0x36
	v_lshl_add_u32 v64, v64, 4, s51
	v_add3_u32 v64, v64, v123, v105
	ds_write_b16 v64, v62 offset:768
	v_add_u32_e32 v62, 0x70, v1
	v_lshrrev_b32_e32 v62, 3, v62
	v_bitop3_b32 v64, v62, v118, 3 bitop3:0x78
	v_lshl_add_u32 v64, v64, 4, s51
	v_add3_u32 v64, v64, v123, v105
	v_add_u32_e32 v74, s46, v118
	v_ashrrev_i32_e32 v75, 31, v74
	v_add_u32_e32 v76, 4, v74
	v_ashrrev_i32_e32 v77, 31, v76
	s_waitcnt vmcnt(0)
; __device__ __forceinline__ unsigned cvt_pk_bf16(float lo, float hi) { unsigned r; asm volatile("v_cvt_pk_bf16_f32 %0, %1, %2" : "=v"(r) : "v"(lo), "v"(hi)); return r; }
; #define LAS __attribute__((address_space(3)))
; __device__ __forceinline__ float bf_lo(unsigned u) { return __uint_as_float(u << 16); }
; __device__ __forceinline__ float bf_hi(unsigned u) { return __uint_as_float(u & 0xffff0000u); }
; #define LBAR() asm volatile("s_waitcnt lgkmcnt(0)\n\ts_barrier" ::: "memory")
; __device__ __forceinline__ void ret_phase(const Params& P, LAS unsigned char* lds, int tid, int lane, int wave, int bid, int G) {
;     ...
; #pragma unroll
;         for (int t = 0; t < 8; ++t) { const int dv = 16 * t + l15; const float gn = P.rgain[h * 128 + dv];
; #pragma unroll
;             for (int i = 0; i < 4; ++i) { const int n = w16 + 4 * g + i; const unsigned wv = cvt_pk_bf16(o[t][i] * rs[i] * gn, 0.f);
;                 *(LAS unsigned short*)(Pt + off256(n, dv >> 3) + 2 * (dv & 7)) = (unsigned short)(wv & 0xffffu); } }
;         LBAR();
; #pragma unroll
;         for (int it = 0; it < 4; ++it) { const int row = w16 + 4 * it + g, ch = l15;
;             const u32x4 ov = *(const LAS u32x4*)(Pt + off256(row, ch));
;             const u32x4 gv = grv[it];
;             u32x4 w; w.x = cvt_pk_bf16(bf_lo(ov.x) * bf_lo(gv.x), bf_hi(ov.x) * bf_hi(gv.x)); w.y = cvt_pk_bf16(bf_lo(ov.y) * bf_lo(gv.y), bf_hi(ov.y) * bf_hi(gv.y));
;             w.z = cvt_pk_bf16(bf_lo(ov.z) * bf_lo(gv.z), bf_hi(ov.z) * bf_hi(gv.z)); w.w = cvt_pk_bf16(bf_lo(ov.w) * bf_lo(gv.w), bf_hi(ov.w) * bf_hi(gv.w));
;             *(u32x4*)(MIX + (tokc + row) * DM + 512 + h * 128 + 8 * ch) = w; }
	v_mul_f32_e32 v50, v50, v63
	v_cvt_pk_bf16_f32 v50, v50, v115
	ds_write_b16 v64, v50
	v_mul_f32_e32 v50, v51, v102
	v_bitop3_b32 v51, v104, v62, 4 bitop3:0x36
	v_lshl_add_u32 v51, v51, 4, s51
	v_mul_f32_e32 v50, v50, v63
	v_add3_u32 v51, v51, v123, v105
	v_cvt_pk_bf16_f32 v50, v50, v115
	ds_write_b16 v51, v50 offset:256
	v_bitop3_b32 v51, v104, v62, 8 bitop3:0x36
	v_mul_f32_e32 v50, v52, v101
	v_lshl_add_u32 v51, v51, 4, s51
	v_mul_f32_e32 v50, v50, v63
	v_add3_u32 v51, v51, v123, v105
	v_cvt_pk_bf16_f32 v50, v50, v115
	ds_write_b16 v51, v50 offset:512
	v_bitop3_b32 v51, v104, v62, 12 bitop3:0x36
	v_mul_f32_e32 v50, v53, v100
	v_lshl_add_u32 v51, v51, 4, s51
	v_mul_f32_e32 v50, v50, v63
	v_add3_u32 v51, v51, v123, v105
	v_cvt_pk_bf16_f32 v50, v50, v115
	ds_write_b16 v51, v50 offset:768
	v_bfe_u32 v51, v118, 2, 2
	v_bitop3_b32 v51, v51, v1, v78 bitop3:0x36
	v_lshlrev_b32_e32 v50, 8, v74
	v_lshlrev_b32_e32 v51, 4, v51
	s_waitcnt lgkmcnt(0)
	v_add3_u32 v50, s51, v51, v50
	ds_read_b128 v[50:53], v50
	v_lshlrev_b32_e32 v64, 16, v70
	v_lshlrev_b32_e32 v62, 3, v1
	v_ashrrev_i32_e32 v63, 31, v62
	s_waitcnt lgkmcnt(0)
	v_lshlrev_b32_e32 v65, 16, v50
	v_mul_f32_e32 v64, v65, v64
	v_and_b32_e32 v50, 0xffff0000, v50
	v_and_b32_e32 v65, 0xffff0000, v70
	v_mul_f32_e32 v50, v50, v65
	v_cvt_pk_bf16_f32 v50, v64, v50
	v_lshlrev_b32_e32 v64, 16, v71
	v_lshlrev_b32_e32 v65, 16, v51
	v_mul_f32_e32 v64, v65, v64
	v_and_b32_e32 v51, 0xffff0000, v51
	v_and_b32_e32 v65, 0xffff0000, v71
	v_mul_f32_e32 v51, v51, v65
	v_cvt_pk_bf16_f32 v51, v64, v51
	v_lshlrev_b32_e32 v64, 16, v72
	v_lshlrev_b32_e32 v65, 16, v52
	v_mul_f32_e32 v64, v65, v64
	v_and_b32_e32 v52, 0xffff0000, v52
	v_and_b32_e32 v65, 0xffff0000, v72
	v_mul_f32_e32 v52, v52, v65
	v_cvt_pk_bf16_f32 v52, v64, v52
	v_lshlrev_b32_e32 v64, 16, v73
	v_lshlrev_b32_e32 v65, 16, v53
	v_mul_f32_e32 v64, v65, v64
	v_and_b32_e32 v53, 0xffff0000, v53
	v_and_b32_e32 v65, 0xffff0000, v73
	v_mul_f32_e32 v53, v53, v65
	v_cvt_pk_bf16_f32 v53, v64, v53
	v_lshl_add_u64 v[64:65], s[40:41], 0, v[74:75]
	v_lshlrev_b64 v[70:71], 1, v[62:63]
	v_bfe_u32 v63, v76, 2, 2
	v_lshlrev_b64 v[64:65], 11, v[64:65]
	v_bitop3_b32 v63, v63, v1, v78 bitop3:0x36
	v_lshl_add_u64 v[64:65], s[22:23], 0, v[64:65]
	v_lshlrev_b32_e32 v62, 8, v76
	v_lshlrev_b32_e32 v63, 4, v63
	v_lshl_add_u64 v[64:65], v[64:65], 0, s[18:19]
	v_add3_u32 v62, s51, v63, v62
	v_lshl_add_u64 v[72:73], v[64:65], 0, v[70:71]
	ds_read_b128 v[62:65], v62
	v_add_co_u32_e32 v72, vcc, s55, v72
	s_nop 1
	v_addc_co_u32_e32 v73, vcc, 0, v73, vcc
	global_store_dwordx4 v[72:73], v[50:53], off offset:1024
	s_nop 1
	v_lshlrev_b32_e32 v50, 16, v66
	s_waitcnt lgkmcnt(0)
	v_lshlrev_b32_e32 v51, 16, v62
	v_mul_f32_e32 v50, v51, v50
	v_and_b32_e32 v51, 0xffff0000, v62
	v_and_b32_e32 v52, 0xffff0000, v66
	v_mul_f32_e32 v51, v51, v52
	v_cvt_pk_bf16_f32 v50, v50, v51
	v_lshlrev_b32_e32 v51, 16, v67
	v_lshlrev_b32_e32 v52, 16, v63
	v_mul_f32_e32 v51, v52, v51
	v_and_b32_e32 v52, 0xffff0000, v63
	v_and_b32_e32 v53, 0xffff0000, v67
	v_mul_f32_e32 v52, v52, v53
	v_cvt_pk_bf16_f32 v51, v51, v52
	v_lshlrev_b32_e32 v52, 16, v68
	v_lshlrev_b32_e32 v53, 16, v64
	v_mul_f32_e32 v52, v53, v52
	v_and_b32_e32 v53, 0xffff0000, v64
	v_and_b32_e32 v62, 0xffff0000, v68
	v_mul_f32_e32 v53, v53, v62
	v_cvt_pk_bf16_f32 v52, v52, v53
	v_lshlrev_b32_e32 v53, 16, v69
	v_lshlrev_b32_e32 v62, 16, v65
	v_mul_f32_e32 v53, v62, v53
	v_and_b32_e32 v62, 0xffff0000, v65
	v_and_b32_e32 v63, 0xffff0000, v69
	v_mul_f32_e32 v62, v62, v63
	v_cvt_pk_bf16_f32 v53, v53, v62
	v_lshl_add_u64 v[62:63], s[40:41], 0, v[76:77]
	v_lshlrev_b64 v[62:63], 11, v[62:63]
	v_lshl_add_u64 v[62:63], s[22:23], 0, v[62:63]
	v_lshl_add_u64 v[62:63], v[62:63], 0, s[18:19]
	v_add_u32_e32 v68, 8, v74
	v_lshl_add_u64 v[66:67], v[62:63], 0, v[70:71]
	v_bfe_u32 v63, v68, 2, 2
	v_bitop3_b32 v63, v63, v1, v78 bitop3:0x36
	v_lshlrev_b32_e32 v62, 8, v68
	v_lshlrev_b32_e32 v63, 4, v63
	v_add3_u32 v62, s51, v63, v62
	ds_read_b128 v[62:65], v62
	v_add_co_u32_e32 v66, vcc, s55, v66
	v_ashrrev_i32_e32 v69, 31, v68
	s_nop 0
	v_addc_co_u32_e32 v67, vcc, 0, v67, vcc
	global_store_dwordx4 v[66:67], v[50:53], off offset:1024
	s_nop 1
	v_lshlrev_b32_e32 v50, 16, v58
	s_waitcnt lgkmcnt(0)
; __device__ __forceinline__ unsigned cvt_pk_bf16(float lo, float hi) { unsigned r; asm volatile("v_cvt_pk_bf16_f32 %0, %1, %2" : "=v"(r) : "v"(lo), "v"(hi)); return r; }
; #define LAS __attribute__((address_space(3)))
; __device__ __forceinline__ float bf_lo(unsigned u) { return __uint_as_float(u << 16); }
; __device__ __forceinline__ float bf_hi(unsigned u) { return __uint_as_float(u & 0xffff0000u); }
; #define LBAR() asm volatile("s_waitcnt lgkmcnt(0)\n\ts_barrier" ::: "memory")
; __device__ __forceinline__ void ret_phase(const Params& P, LAS unsigned char* lds, int tid, int lane, int wave, int bid, int G) {
;     ...
; #pragma unroll
;         for (int it = 0; it < 4; ++it) { const int row = w16 + 4 * it + g, ch = l15;
;             const u32x4 ov = *(const LAS u32x4*)(Pt + off256(row, ch));
;             const u32x4 gv = grv[it];
;             u32x4 w; w.x = cvt_pk_bf16(bf_lo(ov.x) * bf_lo(gv.x), bf_hi(ov.x) * bf_hi(gv.x)); w.y = cvt_pk_bf16(bf_lo(ov.y) * bf_lo(gv.y), bf_hi(ov.y) * bf_hi(gv.y));
;             w.z = cvt_pk_bf16(bf_lo(ov.z) * bf_lo(gv.z), bf_hi(ov.z) * bf_hi(gv.z)); w.w = cvt_pk_bf16(bf_lo(ov.w) * bf_lo(gv.w), bf_hi(ov.w) * bf_hi(gv.w));
;             *(u32x4*)(MIX + (tokc + row) * DM + 512 + h * 128 + 8 * ch) = w; }
;         LBAR();
	v_lshlrev_b32_e32 v51, 16, v62
	v_mul_f32_e32 v50, v51, v50
	v_and_b32_e32 v51, 0xffff0000, v62
	v_and_b32_e32 v52, 0xffff0000, v58
	v_mul_f32_e32 v51, v51, v52
	v_cvt_pk_bf16_f32 v50, v50, v51
	v_lshlrev_b32_e32 v51, 16, v59
	v_lshlrev_b32_e32 v52, 16, v63
	v_mul_f32_e32 v51, v52, v51
	v_and_b32_e32 v52, 0xffff0000, v63
	v_and_b32_e32 v53, 0xffff0000, v59
	v_mul_f32_e32 v52, v52, v53
	v_cvt_pk_bf16_f32 v51, v51, v52
	v_lshlrev_b32_e32 v52, 16, v60
	v_lshlrev_b32_e32 v53, 16, v64
	v_mul_f32_e32 v52, v53, v52
	v_and_b32_e32 v53, 0xffff0000, v64
	v_and_b32_e32 v58, 0xffff0000, v60
	v_mul_f32_e32 v53, v53, v58
	v_cvt_pk_bf16_f32 v52, v52, v53
	v_lshlrev_b32_e32 v53, 16, v61
	v_lshlrev_b32_e32 v58, 16, v65
	v_mul_f32_e32 v53, v58, v53
	v_and_b32_e32 v58, 0xffff0000, v65
	v_and_b32_e32 v59, 0xffff0000, v61
	v_mul_f32_e32 v58, v58, v59
	v_cvt_pk_bf16_f32 v53, v53, v58
	v_lshl_add_u64 v[58:59], s[40:41], 0, v[68:69]
	v_lshlrev_b64 v[58:59], 11, v[58:59]
	v_lshl_add_u64 v[58:59], s[22:23], 0, v[58:59]
	v_lshl_add_u64 v[58:59], v[58:59], 0, s[18:19]
	v_add_u32_e32 v64, 12, v74
	v_lshl_add_u64 v[62:63], v[58:59], 0, v[70:71]
	v_bfe_u32 v59, v64, 2, 2
	v_bitop3_b32 v59, v59, v1, v78 bitop3:0x36
	v_lshlrev_b32_e32 v58, 8, v64
	v_lshlrev_b32_e32 v59, 4, v59
	v_add3_u32 v58, s51, v59, v58
	ds_read_b128 v[58:61], v58
	v_add_co_u32_e32 v62, vcc, s55, v62
	v_ashrrev_i32_e32 v65, 31, v64
	s_nop 0
	v_addc_co_u32_e32 v63, vcc, 0, v63, vcc
	global_store_dwordx4 v[62:63], v[50:53], off offset:1024
	s_nop 1
	v_lshlrev_b32_e32 v50, 16, v54
	s_waitcnt lgkmcnt(0)
	v_lshlrev_b32_e32 v51, 16, v58
	v_mul_f32_e32 v50, v51, v50
	v_and_b32_e32 v51, 0xffff0000, v58
	v_and_b32_e32 v52, 0xffff0000, v54
	v_mul_f32_e32 v51, v51, v52
	v_cvt_pk_bf16_f32 v50, v50, v51
	v_lshlrev_b32_e32 v51, 16, v55
	v_lshlrev_b32_e32 v52, 16, v59
	v_mul_f32_e32 v51, v52, v51
	v_and_b32_e32 v52, 0xffff0000, v59
	v_and_b32_e32 v53, 0xffff0000, v55
	v_mul_f32_e32 v52, v52, v53
	v_cvt_pk_bf16_f32 v51, v51, v52
	v_lshlrev_b32_e32 v52, 16, v56
	v_lshlrev_b32_e32 v53, 16, v60
	v_mul_f32_e32 v52, v53, v52
	v_and_b32_e32 v53, 0xffff0000, v60
	v_and_b32_e32 v54, 0xffff0000, v56
	v_mul_f32_e32 v53, v53, v54
	v_cvt_pk_bf16_f32 v52, v52, v53
	v_lshlrev_b32_e32 v53, 16, v57
	v_lshlrev_b32_e32 v54, 16, v61
	v_mul_f32_e32 v53, v54, v53
	v_and_b32_e32 v54, 0xffff0000, v61
	v_and_b32_e32 v55, 0xffff0000, v57
	v_mul_f32_e32 v54, v54, v55
	v_cvt_pk_bf16_f32 v53, v53, v54
	v_lshl_add_u64 v[54:55], s[40:41], 0, v[64:65]
	v_lshlrev_b64 v[54:55], 11, v[54:55]
	v_lshl_add_u64 v[54:55], s[22:23], 0, v[54:55]
	v_lshl_add_u64 v[54:55], v[54:55], 0, s[18:19]
	v_lshl_add_u64 v[54:55], v[54:55], 0, v[70:71]
	v_add_co_u32_e32 v54, vcc, 0x2000000, v54
	s_nop 1
	v_addc_co_u32_e32 v55, vcc, 0, v55, vcc
	global_store_dwordx4 v[54:55], v[50:53], off offset:1024
	s_waitcnt lgkmcnt(0)
	s_barrier
	s_andn2_b64 vcc, exec, s[42:43]
	s_cbranch_vccz .LBB0_393
